# KB1: attention K tile LDS swizzle matched to CDNA4's 16-lane ds_read_b128 groups (no 2-way conflicts on K reads; +0x80 immediates replaced by v_xor of the address registers); on top of BE1
# speedup vs baseline: 1.0042x; 1.0042x over previous
.LBB0_626:
	v_mov_b32_e32 v4, v0
	s_lshl_b64 s[8:9], s[18:19], 12
	s_add_u32 s8, s4, s8
	v_ashrrev_i32_e32 v167, 6, v4
	v_and_b32_e32 v165, 31, v4
	v_lshlrev_b32_e32 v164, 5, v167
	s_addc_u32 s9, s5, s9
	s_lshl_b32 s18, s30, 8
	v_or_b32_e32 v6, v164, v165
	s_add_u32 s40, s8, s18
	v_ashrrev_i32_e32 v7, 31, v6
	s_addc_u32 s41, s9, 0
	v_bfe_u32 v170, v4, 5, 1
	v_lshlrev_b64 v[6:7], 12, v[6:7]
	v_lshl_add_u64 v[6:7], s[40:41], 0, v[6:7]
	v_lshlrev_b32_e32 v168, 4, v170
	v_mov_b32_e32 v169, v3
	s_lshl_b64 s[8:9], s[16:17], 10
	v_lshl_add_u64 v[6:7], v[6:7], 0, v[168:169]
	v_ashrrev_i32_e32 v5, 4, v4
	s_add_u32 s18, s14, s8
	global_load_dwordx4 v[128:131], v[6:7], off
	global_load_dwordx4 v[124:127], v[6:7], off offset:32
	global_load_dwordx4 v[120:123], v[6:7], off offset:64
	global_load_dwordx4 v[116:119], v[6:7], off offset:96
	global_load_dwordx4 v[112:115], v[6:7], off offset:128
	global_load_dwordx4 v[108:111], v[6:7], off offset:160
	global_load_dwordx4 v[104:107], v[6:7], off offset:192
	global_load_dwordx4 v[100:103], v[6:7], off offset:224
	v_and_b32_e32 v7, 0xfffff8, v5
	v_lshlrev_b32_e32 v8, 1, v5
	s_addc_u32 s19, s15, s9
	s_lshl_b64 s[16:17], s[36:37], 1
	v_lshrrev_b32_e32 v8, 1, v5
	v_and_b32_e32 v9, 3, v5
	v_add_u32_e32 v22, 32, v5
	s_add_u32 s30, s18, s16
	v_and_b32_e32 v8, 7, v5
	v_and_b32_e32 v9, 0xfffff8, v22
	v_lshlrev_b32_e32 v10, 1, v22
	s_addc_u32 s31, s19, s17
	v_lshlrev_b32_e32 v2, 3, v4
	s_add_u32 s8, s28, s8
	v_and_b32_e32 v6, 0x78, v2
	v_lshrrev_b32_e32 v7, 1, v7
	v_bfe_u32 v2, v2, 5, 2
	v_lshrrev_b32_e32 v9, 1, v9
	s_addc_u32 s9, s29, s9
	v_or_b32_e32 v7, v7, v2
	v_lshlrev_b32_e32 v166, 1, v6
	v_or_b32_e32 v2, v9, v2
	s_add_u32 s42, s8, s16
	v_lshlrev_b32_e32 v8, 6, v8
	v_and_b32_e32 v6, 48, v166
	v_lshlrev_b32_e32 v2, 9, v2
	s_addc_u32 s43, s9, s17
	v_lshlrev_b32_e32 v7, 9, v7
	v_or3_b32 v178, v2, v8, v6
	v_lshl_or_b32 v2, v5, 10, v166
	v_or3_b32 v179, v7, v8, v6
	v_lshl_add_u64 v[36:37], s[42:43], 0, v[2:3]
	global_load_dwordx4 v[6:9], v2, s[42:43]
	global_load_dwordx4 v[14:17], v2, s[30:31]
	v_add_co_u32_e32 v10, vcc, s33, v36
	v_lshl_add_u64 v[38:39], s[30:31], 0, v[2:3]
	s_nop 0
	v_addc_co_u32_e32 v11, vcc, 0, v37, vcc
	global_load_dwordx4 v[10:13], v[10:11], off
	v_add_co_u32_e32 v18, vcc, s33, v38
	v_add_u32_e32 v40, 0, v179
	s_nop 0
	v_addc_co_u32_e32 v19, vcc, 0, v39, vcc
	global_load_dwordx4 v[18:21], v[18:19], off
	s_waitcnt vmcnt(0)
	v_lshlrev_b32_e32 v5, 8, v5
	v_add_u32_e32 v41, 0, v178
	s_mov_b32 s8, 0x10000
	v_readfirstlane_b32 s18, v4
	s_waitcnt vmcnt(0)
	ds_write_b128 v40, v[6:9]
	v_and_b32_e32 v6, 0x70, v4
	v_and_b32_e32 v7, 0x100, v4
	v_lshrrev_b32_e32 v7, 1, v7
	v_or_b32_e32 v6, v6, v7
	v_bitop3_b32 v180, v166, v5, v6 bitop3:0xde
	v_add_u32_e32 v5, 0, v180
	ds_write_b128 v41, v[10:13]
	ds_write_b128 v5, v[14:17] offset:49152
	v_lshlrev_b32_e32 v5, 8, v22
	v_bitop3_b32 v181, v166, v5, v6 bitop3:0xde
	v_add_co_u32_e32 v6, vcc, s8, v36
	v_add_u32_e32 v5, 0, v181
	s_nop 0
	v_addc_co_u32_e32 v7, vcc, 0, v37, vcc
	ds_write_b128 v5, v[18:21] offset:49152
	global_load_dwordx4 v[20:23], v[6:7], off
	v_add_co_u32_e32 v6, vcc, 0x18000, v36
	s_nop 1
	v_addc_co_u32_e32 v7, vcc, 0, v37, vcc
	global_load_dwordx4 v[24:27], v[6:7], off
	v_add_co_u32_e32 v6, vcc, 0x10000, v38
	s_nop 1
	v_addc_co_u32_e32 v7, vcc, 0, v39, vcc
	global_load_dwordx4 v[28:31], v[6:7], off
	v_add_co_u32_e32 v6, vcc, 0x18000, v38
	s_nop 1
	v_addc_co_u32_e32 v7, vcc, 0, v39, vcc
	global_load_dwordx4 v[32:35], v[6:7], off
	s_waitcnt lgkmcnt(0)
	s_barrier
	s_and_b32 s8, s18, 0xffffff00
	s_cmpk_lg_i32 s8, 0x100
	s_cbranch_scc1 .LBB0_628
	s_waitcnt lgkmcnt(0)
	s_barrier
.LBB0_628:
	v_and_b32_e32 v5, 0x3fffffc0, v4
	s_add_i32 s8, 0, 0x18000
	v_lshl_add_u32 v171, v5, 2, s8
	s_add_i32 s8, 0, 0xc000
	s_cmp_lg_u32 s8, -1
	v_and_b32_e32 v169, 63, v4
	v_lshlrev_b32_e32 v4, 4, v4
	s_cselect_b32 s8, s8, 0
	v_and_b32_e32 v4, 0x70, v4
	v_and_b32_e32 v8, 16, v165
	v_lshlrev_b32_e32 v8, 3, v8
	v_or_b32_e32 v4, v4, v8
	v_lshl_add_u32 v7, v165, 8, s8
	v_or_b32_e32 v8, 32, v168
	v_xad_u32 v175, v8, v4, v7
	v_or_b32_e32 v8, 64, v168
	v_lshlrev_b32_e32 v5, 4, v169
	v_xad_u32 v176, v8, v4, v7
	v_or_b32_e32 v8, 0x60, v168
	s_mov_b32 s48, 2
	s_mov_b32 s49, 1
	v_lshlrev_b32_e32 v6, 1, v169
	s_mov_b32 s52, 0
	v_xad_u32 v174, v168, v4, v7
	v_xad_u32 v177, v8, v4, v7
	v_lshlrev_b32_e32 v66, 3, v169
	s_movk_i32 s50, 0xc0
	v_and_b32_e32 v67, 0xc0, v5
	v_and_b32_e32 v148, 32, v6
	ds_read_b128 v[4:7], v174 offset:0
	ds_read_b128 v[8:11], v174 offset:0x2000
	ds_read_b128 v[12:15], v175 offset:0
	ds_read_b128 v[42:45], v175 offset:0x2000
	ds_read_b128 v[46:49], v176 offset:0
	ds_read_b128 v[50:53], v176 offset:0x2000
	ds_read_b128 v[54:57], v177 offset:0
	ds_read_b128 v[58:61], v177 offset:0x2000
	s_waitcnt lgkmcnt(4)
	s_nop 0
	v_mfma_f32_32x32x16_bf16 v[84:99], v[4:7], v[128:131], 0
	s_mov_b32 s53, s52
	s_mov_b32 s54, s52
	s_mov_b32 s55, s52
	s_mov_b32 s56, s52
	s_mov_b32 s57, s52
	s_mov_b32 s58, s52
	s_mov_b32 s59, s52
	v_mfma_f32_32x32x16_bf16 v[68:83], v[8:11], v[128:131], 0
	s_mov_b32 s60, s52
	s_mov_b32 s61, s52
	s_mov_b32 s62, s52
	s_mov_b32 s63, s52
	s_mov_b32 s64, s52
	s_mov_b32 s65, s52
	s_mov_b32 s66, s52
	v_mfma_f32_32x32x16_bf16 v[84:99], v[12:15], v[124:127], v[84:99]
	s_mov_b32 s67, s52
	v_mov_b64_e32 v[4:5], s[52:53]
	v_mov_b64_e32 v[6:7], s[54:55]
	v_mov_b64_e32 v[8:9], s[56:57]
	v_mov_b64_e32 v[10:11], s[58:59]
	v_mov_b64_e32 v[12:13], s[60:61]
	v_mov_b64_e32 v[14:15], s[62:63]
	v_mfma_f32_32x32x16_bf16 v[68:83], v[42:45], v[124:127], v[68:83]
	v_mov_b64_e32 v[16:17], s[64:65]
	v_mov_b64_e32 v[18:19], s[66:67]
	v_xor_b32_e32 v174, 0x80, v174
	ds_read_b128 v[42:45], v174 offset:0
	ds_read_b128 v[62:65], v174 offset:0x2000
	v_xor_b32_e32 v175, 0x80, v175
	ds_read_b128 v[132:135], v175 offset:0
	ds_read_b128 v[136:139], v175 offset:0x2000
	s_waitcnt lgkmcnt(4)
	v_mfma_f32_32x32x16_bf16 v[84:99], v[46:49], v[120:123], v[84:99]
	v_mfma_f32_32x32x16_bf16 v[68:83], v[50:53], v[120:123], v[68:83]
	v_mfma_f32_32x32x16_bf16 v[84:99], v[54:57], v[116:119], v[84:99]
	v_mfma_f32_32x32x16_bf16 v[68:83], v[58:61], v[116:119], v[68:83]
	v_xor_b32_e32 v176, 0x80, v176
	ds_read_b128 v[46:49], v176 offset:0
	ds_read_b128 v[50:53], v176 offset:0x2000
	v_xor_b32_e32 v177, 0x80, v177
	ds_read_b128 v[54:57], v177 offset:0
	ds_read_b128 v[58:61], v177 offset:0x2000
	v_xor_b32_e32 v174, 0x80, v174
	v_xor_b32_e32 v175, 0x80, v175
	v_xor_b32_e32 v176, 0x80, v176
	v_xor_b32_e32 v177, 0x80, v177
	s_waitcnt lgkmcnt(4)
	v_mfma_f32_32x32x16_bf16 v[84:99], v[42:45], v[112:115], v[84:99]
	v_mfma_f32_32x32x16_bf16 v[68:83], v[62:65], v[112:115], v[68:83]
	v_mfma_f32_32x32x16_bf16 v[84:99], v[132:135], v[108:111], v[84:99]
	v_mfma_f32_32x32x16_bf16 v[68:83], v[136:139], v[108:111], v[68:83]
	s_waitcnt lgkmcnt(0)
	v_mfma_f32_32x32x16_bf16 v[84:99], v[46:49], v[104:107], v[84:99]
	v_mfma_f32_32x32x16_bf16 v[68:83], v[50:53], v[104:107], v[68:83]
	v_mfma_f32_32x32x16_bf16 v[84:99], v[54:57], v[100:103], v[84:99]
	v_mfma_f32_32x32x16_bf16 v[68:83], v[58:61], v[100:103], v[68:83]
	s_add_i32 s8, 0, 0x10000
	s_waitcnt vmcnt(0)
	s_waitcnt vmcnt(3)
	ds_write_b128 v40, v[20:23] offset:16384
	s_waitcnt vmcnt(2)
	ds_write_b128 v41, v[24:27] offset:16384
	v_add_u32_e32 v20, s8, v180
	s_waitcnt vmcnt(1)
	ds_write_b128 v20, v[28:31]
	v_add_u32_e32 v20, s8, v181
	s_waitcnt vmcnt(0)
	ds_write_b128 v20, v[32:35]
	v_add_co_u32_e32 v20, vcc, s22, v38
	s_nop 1
	v_addc_co_u32_e32 v21, vcc, 0, v39, vcc
	global_load_dwordx4 v[132:135], v[20:21], off
	v_add_co_u32_e32 v20, vcc, s24, v38
	s_nop 1
	v_addc_co_u32_e32 v21, vcc, 0, v39, vcc
	global_load_dwordx4 v[140:143], v[20:21], off
	v_add_co_u32_e32 v20, vcc, s22, v36
	s_nop 1
	v_addc_co_u32_e32 v21, vcc, 0, v37, vcc
	global_load_dwordx4 v[136:139], v[20:21], off
	v_add_co_u32_e32 v20, vcc, s24, v36
	s_nop 1
	v_addc_co_u32_e32 v21, vcc, 0, v37, vcc
	global_load_dwordx4 v[144:147], v[20:21], off
	s_waitcnt lgkmcnt(0)
	s_barrier
	s_movk_i32 s8, 0x118
	s_cmp_lg_u32 0, -1
	v_and_or_b32 v20, v66, s8, v148
	s_cselect_b32 s8, 0, 0
	v_add3_u32 v173, v67, s8, v20
	v_mov_b64_e32 v[66:67], v[18:19]
	v_mov_b64_e32 v[50:51], v[18:19]
	v_mov_b64_e32 v[34:35], v[18:19]
	v_cmp_gt_u32_e64 s[38:39], 32, v169
	v_lshl_add_u32 v172, v165, 2, v171
	v_mov_b32_e32 v183, 0
	v_mov_b32_e32 v182, 0xf149f2ca
	v_mov_b64_e32 v[64:65], v[16:17]
	v_mov_b64_e32 v[62:63], v[14:15]
	v_mov_b64_e32 v[60:61], v[12:13]
	v_mov_b64_e32 v[58:59], v[10:11]
	v_mov_b64_e32 v[56:57], v[8:9]
	v_mov_b64_e32 v[54:55], v[6:7]
	v_mov_b64_e32 v[52:53], v[4:5]
	v_mov_b64_e32 v[48:49], v[16:17]
	v_mov_b64_e32 v[46:47], v[14:15]
	v_mov_b64_e32 v[44:45], v[12:13]
	v_mov_b64_e32 v[42:43], v[10:11]
	v_mov_b64_e32 v[40:41], v[8:9]
	v_mov_b64_e32 v[38:39], v[6:7]
	v_mov_b64_e32 v[36:37], v[4:5]
	v_mov_b64_e32 v[32:33], v[16:17]
	v_mov_b64_e32 v[30:31], v[14:15]
	v_mov_b64_e32 v[28:29], v[12:13]
	v_mov_b64_e32 v[26:27], v[10:11]
	v_mov_b64_e32 v[24:25], v[8:9]
	v_mov_b64_e32 v[22:23], v[6:7]
	v_mov_b64_e32 v[20:21], v[4:5]
	s_mov_b32 s51, 2
	s_branch .LBB0_629

.LBB0_633:
	s_waitcnt lgkmcnt(0)
	s_barrier
	v_lshl_add_u32 v187, s53, 14, v173
	ds_read_b64_tr_b16 v[188:189], v187 offset:0
	ds_read_b64_tr_b16 v[190:191], v187 offset:0x800
	ds_read_b64_tr_b16 v[192:193], v187 offset:0x1000
	ds_read_b64_tr_b16 v[194:195], v187 offset:0x1800
	ds_read_b64_tr_b16 v[196:197], v187 offset:0x2000
	ds_read_b64_tr_b16 v[198:199], v187 offset:0x2800
	ds_read_b64_tr_b16 v[200:201], v187 offset:0x3000
	ds_read_b64_tr_b16 v[202:203], v187 offset:0x3800
	s_lshl_b32 s52, s49, 14
	v_add_u32_e32 v208, s52, v174
	ds_read_b128 v[68:71], v208 offset:0
	ds_read_b128 v[72:75], v208 offset:0x2000
	v_add_u32_e32 v209, s52, v175
	ds_read_b128 v[204:207], v209 offset:0
	ds_read_b128 v[216:219], v209 offset:0x2000
	v_add_u32_e32 v210, s52, v176
	ds_read_b128 v[220:223], v210 offset:0
	ds_read_b128 v[224:227], v210 offset:0x2000
	v_add_u32_e32 v211, s52, v177
	ds_read_b128 v[228:231], v211 offset:0
	ds_read_b128 v[232:235], v211 offset:0x2000
	s_waitcnt lgkmcnt(4)
	v_mfma_f32_32x32x16_bf16 v[84:99], v[68:71], v[128:131], 0
	v_mfma_f32_32x32x16_bf16 v[68:83], v[72:75], v[128:131], 0
	v_mfma_f32_32x32x16_bf16 v[84:99], v[204:207], v[124:127], v[84:99]
	v_mfma_f32_32x32x16_bf16 v[68:83], v[216:219], v[124:127], v[68:83]
	v_xor_b32_e32 v208, 0x80, v208
	ds_read_b128 v[204:207], v208 offset:0
	ds_read_b128 v[216:219], v208 offset:0x2000
	v_xor_b32_e32 v209, 0x80, v209
	ds_read_b128 v[236:239], v209 offset:0
	ds_read_b128 v[242:245], v209 offset:0x2000
	s_waitcnt lgkmcnt(4)
	v_mfma_f32_32x32x16_bf16 v[84:99], v[220:223], v[120:123], v[84:99]
	v_mfma_f32_32x32x16_bf16 v[68:83], v[224:227], v[120:123], v[68:83]
	v_mfma_f32_32x32x16_bf16 v[84:99], v[228:231], v[116:119], v[84:99]
	v_mfma_f32_32x32x16_bf16 v[68:83], v[232:235], v[116:119], v[68:83]
	v_xor_b32_e32 v210, 0x80, v210
	ds_read_b128 v[220:223], v210 offset:0
	ds_read_b128 v[224:227], v210 offset:0x2000
	v_xor_b32_e32 v211, 0x80, v211
	ds_read_b128 v[228:231], v211 offset:0
	ds_read_b128 v[232:235], v211 offset:0x2000
	s_waitcnt lgkmcnt(4)
	v_mfma_f32_32x32x16_bf16 v[84:99], v[204:207], v[112:115], v[84:99]
	v_mfma_f32_32x32x16_bf16 v[68:83], v[216:219], v[112:115], v[68:83]
	v_mfma_f32_32x32x16_bf16 v[84:99], v[236:239], v[108:111], v[84:99]
	v_mfma_f32_32x32x16_bf16 v[68:83], v[242:245], v[108:111], v[68:83]
	s_waitcnt lgkmcnt(0)
	v_mfma_f32_32x32x16_bf16 v[84:99], v[220:223], v[104:107], v[84:99]
	v_mfma_f32_32x32x16_bf16 v[68:83], v[224:227], v[104:107], v[68:83]
	v_mfma_f32_32x32x16_bf16 v[84:99], v[228:231], v[100:103], v[84:99]
	v_mfma_f32_32x32x16_bf16 v[68:83], v[232:235], v[100:103], v[68:83]
	ds_read_b64_tr_b16 v[204:205], v187 offset:0x200
	ds_read_b64_tr_b16 v[206:207], v187 offset:0xa00
	ds_read_b64_tr_b16 v[216:217], v187 offset:0x1200
	ds_read_b64_tr_b16 v[218:219], v187 offset:0x1a00
	ds_read_b64_tr_b16 v[220:221], v187 offset:0x2200
	ds_read_b64_tr_b16 v[222:223], v187 offset:0x2a00
	ds_read_b64_tr_b16 v[224:225], v187 offset:0x3200
	ds_read_b64_tr_b16 v[226:227], v187 offset:0x3a00
	s_waitcnt lgkmcnt(8)
	v_mfma_f32_32x32x16_bf16 v[4:19], v[148:151], v[188:191], v[4:19]
	s_lshl_b32 s19, s51, 14
	s_add_i32 s8, s19, 0
	v_add_u32_e32 v236, s8, v179
	s_waitcnt vmcnt(0)
	v_mfma_f32_32x32x16_bf16 v[4:19], v[152:155], v[192:195], v[4:19]
	ds_write_b128 v236, v[144:147]
	v_add_u32_e32 v236, s8, v178
	v_mfma_f32_32x32x16_bf16 v[4:19], v[156:159], v[196:199], v[4:19]
	ds_write_b128 v236, v[136:139]
	v_add_u32_e32 v236, s8, v180
	v_mfma_f32_32x32x16_bf16 v[4:19], v[160:163], v[200:203], v[4:19]
	ds_read_b64_tr_b16 v[188:189], v187 offset:0x400
	ds_read_b64_tr_b16 v[190:191], v187 offset:0xc00
	ds_read_b64_tr_b16 v[192:193], v187 offset:0x1400
	ds_read_b64_tr_b16 v[194:195], v187 offset:0x1c00
	ds_read_b64_tr_b16 v[196:197], v187 offset:0x2400
	ds_read_b64_tr_b16 v[198:199], v187 offset:0x2c00
	ds_read_b64_tr_b16 v[200:201], v187 offset:0x3400
	ds_read_b64_tr_b16 v[202:203], v187 offset:0x3c00
	s_waitcnt lgkmcnt(10)
	v_mfma_f32_32x32x16_bf16 v[52:67], v[148:151], v[204:207], v[52:67]
	ds_write_b128 v236, v[140:143] offset:49152
	v_add_u32_e32 v236, s8, v181
	v_mfma_f32_32x32x16_bf16 v[52:67], v[152:155], v[216:219], v[52:67]
	ds_write_b128 v236, v[132:135] offset:49152
	s_add_i32 s48, s48, 1
	v_mfma_f32_32x32x16_bf16 v[52:67], v[156:159], v[220:223], v[52:67]
	s_sub_i32 s8, s50, s47
	s_min_u32 s36, s50, s8
	s_lshl_b64 s[8:9], s[36:37], 10
	s_cmp_lt_u32 s50, s47
	s_cselect_b32 s16, s30, s20
	s_cselect_b32 s17, s31, s21
	v_mfma_f32_32x32x16_bf16 v[52:67], v[160:163], v[224:227], v[52:67]
	ds_read_b64_tr_b16 v[204:205], v187 offset:0x600
	ds_read_b64_tr_b16 v[206:207], v187 offset:0xe00
	ds_read_b64_tr_b16 v[216:217], v187 offset:0x1600
	ds_read_b64_tr_b16 v[218:219], v187 offset:0x1e00
	ds_read_b64_tr_b16 v[220:221], v187 offset:0x2600
	ds_read_b64_tr_b16 v[222:223], v187 offset:0x2e00
	ds_read_b64_tr_b16 v[224:225], v187 offset:0x3600
	ds_read_b64_tr_b16 v[226:227], v187 offset:0x3e00
	s_waitcnt lgkmcnt(10)
	v_mfma_f32_32x32x16_bf16 v[36:51], v[148:151], v[188:191], v[36:51]
	s_cselect_b32 s36, s42, s26
	s_cselect_b32 s54, s43, s27
	s_add_u32 s16, s16, s8
	s_addc_u32 s17, s17, s9
	s_add_u32 s8, s36, s8
	s_addc_u32 s9, s54, s9
	v_mfma_f32_32x32x16_bf16 v[36:51], v[152:155], v[192:195], v[36:51]
	global_load_dwordx4 v[144:147], v2, s[8:9]
	s_add_u32 s8, s8, 0x8000
	s_addc_u32 s9, s9, 0
	v_mfma_f32_32x32x16_bf16 v[36:51], v[156:159], v[196:199], v[36:51]
	global_load_dwordx4 v[136:139], v2, s[8:9]
	global_load_dwordx4 v[140:143], v2, s[16:17]
	v_mfma_f32_32x32x16_bf16 v[36:51], v[160:163], v[200:203], v[36:51]
	s_add_u32 s16, s16, 0x8000
	s_addc_u32 s17, s17, 0
	global_load_dwordx4 v[132:135], v2, s[16:17]
	s_waitcnt lgkmcnt(0)
	v_mfma_f32_32x32x16_bf16 v[20:35], v[148:151], v[204:207], v[20:35]
	v_mfma_f32_32x32x16_bf16 v[20:35], v[152:155], v[216:219], v[20:35]
	v_mfma_f32_32x32x16_bf16 v[20:35], v[156:159], v[220:223], v[20:35]
	v_mfma_f32_32x32x16_bf16 v[20:35], v[160:163], v[224:227], v[20:35]

.LBB0_641:
	s_waitcnt lgkmcnt(0)
	s_barrier
	v_add_u32_e32 v202, s52, v173
	ds_read_b64_tr_b16 v[152:153], v202 offset:0
	ds_read_b64_tr_b16 v[154:155], v202 offset:0x800
	ds_read_b64_tr_b16 v[156:157], v202 offset:0x1000
	ds_read_b64_tr_b16 v[158:159], v202 offset:0x1800
	ds_read_b64_tr_b16 v[160:161], v202 offset:0x2000
	ds_read_b64_tr_b16 v[162:163], v202 offset:0x2800
	ds_read_b64_tr_b16 v[178:179], v202 offset:0x3000
	ds_read_b64_tr_b16 v[180:181], v202 offset:0x3800
	v_add_u32_e32 v203, s19, v174
	ds_read_b128 v[68:71], v203 offset:0
	ds_read_b128 v[72:75], v203 offset:0x2000
	v_add_u32_e32 v204, s19, v175
	v_add_u32_e32 v205, s19, v176
	v_add_u32_e32 v206, s19, v177
	ds_read_b128 v[174:177], v204 offset:0
	ds_read_b128 v[182:185], v204 offset:0x2000
	ds_read_b128 v[186:189], v205 offset:0
	ds_read_b128 v[190:193], v205 offset:0x2000
	ds_read_b128 v[194:197], v206 offset:0
	ds_read_b128 v[198:201], v206 offset:0x2000
	s_waitcnt lgkmcnt(4)
	v_mfma_f32_32x32x16_bf16 v[84:99], v[68:71], v[128:131], 0
	v_mfma_f32_32x32x16_bf16 v[68:83], v[72:75], v[128:131], 0
	v_mfma_f32_32x32x16_bf16 v[84:99], v[174:177], v[124:127], v[84:99]
	v_mfma_f32_32x32x16_bf16 v[68:83], v[182:185], v[124:127], v[68:83]
	v_xor_b32_e32 v203, 0x80, v203
	ds_read_b128 v[124:127], v203 offset:0
	ds_read_b128 v[128:131], v203 offset:0x2000
	v_xor_b32_e32 v204, 0x80, v204
	ds_read_b128 v[174:177], v204 offset:0
	ds_read_b128 v[182:185], v204 offset:0x2000
	s_waitcnt lgkmcnt(4)
	v_mfma_f32_32x32x16_bf16 v[84:99], v[186:189], v[120:123], v[84:99]
	v_mfma_f32_32x32x16_bf16 v[68:83], v[190:193], v[120:123], v[68:83]
	v_mfma_f32_32x32x16_bf16 v[84:99], v[194:197], v[116:119], v[84:99]
	v_mfma_f32_32x32x16_bf16 v[68:83], v[198:201], v[116:119], v[68:83]
	v_xor_b32_e32 v205, 0x80, v205
	ds_read_b128 v[116:119], v205 offset:0
	ds_read_b128 v[120:123], v205 offset:0x2000
	v_xor_b32_e32 v206, 0x80, v206
	ds_read_b128 v[186:189], v206 offset:0
	ds_read_b128 v[190:193], v206 offset:0x2000
	s_waitcnt lgkmcnt(4)
	v_mfma_f32_32x32x16_bf16 v[84:99], v[124:127], v[112:115], v[84:99]
	v_mfma_f32_32x32x16_bf16 v[68:83], v[128:131], v[112:115], v[68:83]
	v_mfma_f32_32x32x16_bf16 v[84:99], v[174:177], v[108:111], v[84:99]
	v_mfma_f32_32x32x16_bf16 v[68:83], v[182:185], v[108:111], v[68:83]
	s_waitcnt lgkmcnt(0)
	v_mfma_f32_32x32x16_bf16 v[84:99], v[116:119], v[104:107], v[84:99]
	v_mfma_f32_32x32x16_bf16 v[68:83], v[120:123], v[104:107], v[68:83]
	v_mfma_f32_32x32x16_bf16 v[84:99], v[186:189], v[100:103], v[84:99]
	v_mfma_f32_32x32x16_bf16 v[68:83], v[190:193], v[100:103], v[68:83]
	ds_read_b64_tr_b16 v[100:101], v202 offset:0x200
	ds_read_b64_tr_b16 v[102:103], v202 offset:0xa00
	ds_read_b64_tr_b16 v[104:105], v202 offset:0x1200
	ds_read_b64_tr_b16 v[106:107], v202 offset:0x1a00
	ds_read_b64_tr_b16 v[108:109], v202 offset:0x2200
	ds_read_b64_tr_b16 v[110:111], v202 offset:0x2a00
	ds_read_b64_tr_b16 v[112:113], v202 offset:0x3200
	ds_read_b64_tr_b16 v[114:115], v202 offset:0x3a00
	s_waitcnt lgkmcnt(8)
	v_mfma_f32_32x32x16_bf16 v[4:19], v[132:135], v[152:155], v[4:19]
	v_mfma_f32_32x32x16_bf16 v[4:19], v[136:139], v[156:159], v[4:19]
	v_mfma_f32_32x32x16_bf16 v[4:19], v[140:143], v[160:163], v[4:19]
	v_mfma_f32_32x32x16_bf16 v[4:19], v[144:147], v[178:181], v[4:19]
	ds_read_b64_tr_b16 v[116:117], v202 offset:0x400
	ds_read_b64_tr_b16 v[118:119], v202 offset:0xc00
	ds_read_b64_tr_b16 v[120:121], v202 offset:0x1400
	ds_read_b64_tr_b16 v[122:123], v202 offset:0x1c00
	ds_read_b64_tr_b16 v[124:125], v202 offset:0x2400
	ds_read_b64_tr_b16 v[126:127], v202 offset:0x2c00
	ds_read_b64_tr_b16 v[128:129], v202 offset:0x3400
	ds_read_b64_tr_b16 v[130:131], v202 offset:0x3c00
	s_waitcnt lgkmcnt(8)
	v_mfma_f32_32x32x16_bf16 v[52:67], v[132:135], v[100:103], v[52:67]
	v_mfma_f32_32x32x16_bf16 v[52:67], v[136:139], v[104:107], v[52:67]
	v_mfma_f32_32x32x16_bf16 v[52:67], v[140:143], v[108:111], v[52:67]
	v_mfma_f32_32x32x16_bf16 v[52:67], v[144:147], v[112:115], v[52:67]
	ds_read_b64_tr_b16 v[100:101], v202 offset:0x600
	ds_read_b64_tr_b16 v[102:103], v202 offset:0xe00
	ds_read_b64_tr_b16 v[104:105], v202 offset:0x1600
	ds_read_b64_tr_b16 v[106:107], v202 offset:0x1e00
	ds_read_b64_tr_b16 v[108:109], v202 offset:0x2600
	ds_read_b64_tr_b16 v[110:111], v202 offset:0x2e00
	ds_read_b64_tr_b16 v[112:113], v202 offset:0x3600
	ds_read_b64_tr_b16 v[114:115], v202 offset:0x3e00
	s_waitcnt lgkmcnt(8)
	v_mfma_f32_32x32x16_bf16 v[36:51], v[132:135], v[116:119], v[36:51]
	v_mfma_f32_32x32x16_bf16 v[36:51], v[136:139], v[120:123], v[36:51]
	v_mfma_f32_32x32x16_bf16 v[36:51], v[140:143], v[124:127], v[36:51]
	v_mfma_f32_32x32x16_bf16 v[36:51], v[144:147], v[128:131], v[36:51]
	s_waitcnt lgkmcnt(0)
	v_mfma_f32_32x32x16_bf16 v[20:35], v[132:135], v[100:103], v[20:35]
	v_mfma_f32_32x32x16_bf16 v[20:35], v[136:139], v[104:107], v[20:35]
	v_mfma_f32_32x32x16_bf16 v[20:35], v[140:143], v[108:111], v[20:35]
	v_mfma_f32_32x32x16_bf16 v[20:35], v[144:147], v[112:115], v[20:35]
	s_waitcnt lgkmcnt(0)
	s_barrier
	v_max_f32_e32 v100, v85, v85
	v_max_f32_e32 v101, v84, v84
	v_max_f32_e32 v100, v101, v100
	v_max3_f32 v100, v100, v86, v87
	v_max3_f32 v100, v100, v88, v89
	v_max3_f32 v100, v100, v90, v91
	v_max3_f32 v100, v100, v92, v93
	v_max3_f32 v100, v100, v94, v95
	v_max3_f32 v100, v100, v96, v97
	v_max3_f32 v100, v100, v98, v99
	v_max3_f32 v100, v100, v68, v69
	v_max3_f32 v100, v100, v70, v71
	v_max3_f32 v100, v100, v72, v73
	v_max3_f32 v100, v100, v74, v75
	v_max3_f32 v100, v100, v76, v77
	v_max3_f32 v100, v100, v78, v79
	v_max3_f32 v100, v100, v80, v81
	v_max3_f32 v100, v100, v82, v83
	v_mov_b32_e32 v101, v100
	s_nop 1
	v_permlane32_swap_b32_e32 v100, v101
	v_max_f32_e32 v101, v101, v101
	v_max_f32_e32 v100, v100, v100
	v_max_f32_e32 v100, v100, v101
	v_sub_f32_e32 v101, v100, v151
	v_cmp_ge_f32_e32 vcc, s23, v101
	s_cmp_eq_u64 vcc, exec
	v_max_f32_e32 v101, v151, v151
	s_cselect_b64 vcc, -1, 0
	v_max_f32_e32 v101, v101, v100
	v_sub_f32_e32 v100, v151, v101
	v_cndmask_b32_e32 v101, v101, v151, vcc
	v_mul_f32_e32 v101, 0xbe0293ee, v101
	v_fmamk_f32 v84, v84, 0x3e0293ee, v101
	v_fmamk_f32 v85, v85, 0x3e0293ee, v101
	v_fmamk_f32 v86, v86, 0x3e0293ee, v101
	v_fmamk_f32 v87, v87, 0x3e0293ee, v101
	v_fmamk_f32 v88, v88, 0x3e0293ee, v101
	v_fmamk_f32 v89, v89, 0x3e0293ee, v101
	v_fmamk_f32 v90, v90, 0x3e0293ee, v101
	v_fmamk_f32 v91, v91, 0x3e0293ee, v101
	v_fmamk_f32 v92, v92, 0x3e0293ee, v101
	v_fmamk_f32 v93, v93, 0x3e0293ee, v101
	v_fmamk_f32 v94, v94, 0x3e0293ee, v101
	v_fmamk_f32 v95, v95, 0x3e0293ee, v101
	v_fmamk_f32 v96, v96, 0x3e0293ee, v101
	v_fmamk_f32 v97, v97, 0x3e0293ee, v101
	v_fmamk_f32 v98, v98, 0x3e0293ee, v101
	v_fmamk_f32 v99, v99, 0x3e0293ee, v101
	v_fmamk_f32 v68, v68, 0x3e0293ee, v101
	v_fmamk_f32 v69, v69, 0x3e0293ee, v101
	v_fmamk_f32 v70, v70, 0x3e0293ee, v101
	v_fmamk_f32 v71, v71, 0x3e0293ee, v101
	v_fmamk_f32 v72, v72, 0x3e0293ee, v101
	v_fmamk_f32 v73, v73, 0x3e0293ee, v101
	v_fmamk_f32 v74, v74, 0x3e0293ee, v101
	v_fmamk_f32 v75, v75, 0x3e0293ee, v101
	v_fmamk_f32 v76, v76, 0x3e0293ee, v101
	v_fmamk_f32 v77, v77, 0x3e0293ee, v101
	v_fmamk_f32 v78, v78, 0x3e0293ee, v101
	v_fmamk_f32 v79, v79, 0x3e0293ee, v101
	v_fmamk_f32 v80, v80, 0x3e0293ee, v101
	v_fmamk_f32 v81, v81, 0x3e0293ee, v101
	v_fmamk_f32 v82, v82, 0x3e0293ee, v101
	v_fmac_f32_e32 v101, 0x3e0293ee, v83
	v_exp_f32_e32 v83, v84
	v_exp_f32_e32 v102, v85
	v_exp_f32_e32 v86, v86
	v_exp_f32_e32 v87, v87
	v_exp_f32_e32 v88, v88
	v_exp_f32_e32 v103, v68
	v_add_f32_e32 v68, 0, v83
	v_exp_f32_e32 v89, v89
	v_add_f32_e32 v68, v102, v68
	v_exp_f32_e32 v90, v90
	v_add_f32_e32 v68, v86, v68
	v_exp_f32_e32 v91, v91
	v_add_f32_e32 v68, v87, v68
	v_exp_f32_e32 v92, v92
	v_add_f32_e32 v68, v88, v68
	v_exp_f32_e32 v93, v93
	v_add_f32_e32 v68, v89, v68
	v_exp_f32_e32 v94, v94
	v_add_f32_e32 v68, v90, v68
	v_exp_f32_e32 v95, v95
	v_add_f32_e32 v68, v91, v68
	v_exp_f32_e32 v96, v96
	v_add_f32_e32 v68, v92, v68
	v_exp_f32_e32 v97, v97
	v_add_f32_e32 v68, v93, v68
	v_exp_f32_e32 v98, v98
	v_add_f32_e32 v68, v94, v68
	v_exp_f32_e32 v99, v99
	v_add_f32_e32 v68, v95, v68
	v_add_f32_e32 v68, v96, v68
	v_exp_f32_e32 v104, v69
	v_add_f32_e32 v68, v97, v68
	v_exp_f32_e32 v105, v70
	v_add_f32_e32 v68, v98, v68
	v_exp_f32_e32 v106, v71
	v_add_f32_e32 v68, v99, v68
	v_exp_f32_e32 v107, v72
	v_add_f32_e32 v68, v103, v68
	v_exp_f32_e32 v108, v73
	v_add_f32_e32 v68, v104, v68
	v_exp_f32_e32 v109, v74
	v_add_f32_e32 v68, v105, v68
	v_exp_f32_e32 v110, v75
	v_add_f32_e32 v68, v106, v68
	v_exp_f32_e32 v111, v76
	v_add_f32_e32 v68, v107, v68
	v_exp_f32_e32 v112, v77
	v_add_f32_e32 v68, v108, v68
	v_exp_f32_e32 v113, v78
	v_add_f32_e32 v68, v109, v68
	v_exp_f32_e32 v114, v79
	v_add_f32_e32 v68, v110, v68
	v_exp_f32_e32 v115, v80
	v_add_f32_e32 v68, v111, v68
	v_exp_f32_e32 v116, v81
	v_add_f32_e32 v68, v112, v68
	v_exp_f32_e32 v117, v82
	v_add_f32_e32 v68, v113, v68
	v_mul_f32_e32 v100, 0x3e0293ee, v100
	v_exp_f32_e32 v101, v101
	v_add_f32_e32 v68, v114, v68
	v_exp_f32_e32 v100, v100
	v_add_f32_e32 v68, v115, v68
	v_add_f32_e32 v68, v116, v68
	v_add_f32_e32 v68, v117, v68
	v_add_f32_e32 v84, v101, v68
	v_cndmask_b32_e64 v100, v100, 1.0, vcc
	v_mov_b32_e32 v85, v84
	v_cvt_pk_bf16_f32 v68, v83, v102
	v_cvt_pk_bf16_f32 v69, v86, v87
	v_cvt_pk_bf16_f32 v70, v88, v89
	v_cvt_pk_bf16_f32 v71, v90, v91
	v_cvt_pk_bf16_f32 v72, v92, v93
	v_cvt_pk_bf16_f32 v73, v94, v95
	v_cvt_pk_bf16_f32 v74, v96, v97
	v_cvt_pk_bf16_f32 v75, v98, v99
	v_cvt_pk_bf16_f32 v76, v103, v104
	v_cvt_pk_bf16_f32 v77, v105, v106
	v_cvt_pk_bf16_f32 v78, v107, v108
	v_cvt_pk_bf16_f32 v79, v109, v110
	v_cvt_pk_bf16_f32 v80, v111, v112
	v_cvt_pk_bf16_f32 v81, v113, v114
	v_cvt_pk_bf16_f32 v82, v115, v116
	v_cvt_pk_bf16_f32 v83, v117, v101
	s_nop 1
	v_permlane32_swap_b32_e32 v84, v85
	v_cmp_gt_f32_e32 vcc, 1.0, v100
	s_cbranch_vccz .LBB0_645
	s_and_saveexec_b64 s[16:17], s[38:39]
	ds_write_b32 v172, v100 offset:128
	s_or_b64 exec, exec, s[16:17]
	s_waitcnt lgkmcnt(0)
	v_add_u32_e32 v98, v171, v168
	ds_read_b128 v[86:89], v98 offset:224
	ds_read_b128 v[90:93], v98 offset:192
	ds_read_b128 v[94:97], v98 offset:160
	ds_read_b128 v[102:105], v98 offset:128
	s_waitcnt lgkmcnt(3)
	v_pk_mul_f32 v[16:17], v[16:17], v[86:87]
	s_waitcnt lgkmcnt(2)
	v_pk_mul_f32 v[12:13], v[12:13], v[90:91]
	s_waitcnt lgkmcnt(1)
	v_pk_mul_f32 v[8:9], v[8:9], v[94:95]
	v_pk_mul_f32 v[18:19], v[18:19], v[88:89]
	v_pk_mul_f32 v[14:15], v[14:15], v[92:93]
	v_pk_mul_f32 v[10:11], v[10:11], v[96:97]
	s_waitcnt lgkmcnt(0)
	v_pk_mul_f32 v[6:7], v[6:7], v[104:105]
	v_pk_mul_f32 v[4:5], v[4:5], v[102:103]
	v_pk_mul_f32 v[64:65], v[64:65], v[86:87]
	v_pk_mul_f32 v[60:61], v[60:61], v[90:91]
	v_pk_mul_f32 v[56:57], v[56:57], v[94:95]
	v_pk_mul_f32 v[66:67], v[66:67], v[88:89]
	v_pk_mul_f32 v[62:63], v[62:63], v[92:93]
	v_pk_mul_f32 v[58:59], v[58:59], v[96:97]
	v_pk_mul_f32 v[54:55], v[54:55], v[104:105]
	v_pk_mul_f32 v[52:53], v[52:53], v[102:103]
	v_pk_mul_f32 v[48:49], v[48:49], v[86:87]
	v_pk_mul_f32 v[44:45], v[44:45], v[90:91]
	v_pk_mul_f32 v[40:41], v[40:41], v[94:95]
	v_pk_mul_f32 v[50:51], v[50:51], v[88:89]
	v_pk_mul_f32 v[46:47], v[46:47], v[92:93]
	v_pk_mul_f32 v[42:43], v[42:43], v[96:97]
	v_pk_mul_f32 v[38:39], v[38:39], v[104:105]
	v_pk_mul_f32 v[36:37], v[36:37], v[102:103]
	v_pk_mul_f32 v[32:33], v[32:33], v[86:87]
	v_pk_mul_f32 v[28:29], v[28:29], v[90:91]
	v_pk_mul_f32 v[24:25], v[24:25], v[94:95]
	v_pk_mul_f32 v[34:35], v[34:35], v[88:89]
	v_pk_mul_f32 v[30:31], v[30:31], v[92:93]
	v_pk_mul_f32 v[26:27], v[26:27], v[96:97]
	v_pk_mul_f32 v[22:23], v[22:23], v[104:105]
	v_pk_mul_f32 v[20:21], v[20:21], v[102:103]
